# attention queue: ticket->unit mapping permuted so the four (softmax half, value half) units of one (batch, head) run on workgroups of the same XCD at the same time (K and V streams shared through that
# baseline (speedup 1.0000x reference)
; __device__ __forceinline__ int lane_id_asm() { int l; asm volatile("v_mbcnt_lo_u32_b32 %0, -1, 0\n\tv_mbcnt_hi_u32_b32 %0, -1, %0" : "=v"(l)); return l; }
; #define WAIT_BAR(N) asm volatile("s_waitcnt vmcnt(" #N ") lgkmcnt(0)\n\ts_barrier":::"memory")
; template<int THRL> __device__ __forceinline__ void attn_unit(int b,int h,int qb,const bf16*Q,const bf16*__restrict__ K,const bf16*__restrict__ V,bf16*O,char*shm,const int wid){
;   const int lane=lane_id_asm(),tid=wid*64+lane,r32=lane&31,hi=lane>>5;
;   const long rowbase=(long)b*SEQ; const int q0=qb*QB;
;   const int qcol=(h>>1)*64, kcol=512+(h>>1)*64, vcol=1024+(h>>2)*128+(h&1)*64, ocol=h*64;
;   const bf16*Qw=Q+(rowbase+q0+wid*QBLK)*PD+qcol;
;   const bf16*Kh=K+rowbase*PD+kcol,*Vh=V+rowbase*PD+vcol;
;   const unsigned lds0=(unsigned)(uintptr_t)shm;
;   float*wsf=(float*)(shm+LDS_WS)+wid*64;
;   const bf16*ksrc=Kh+(long)lane*PD+wid*8;
;   const bf16*vsrc=Vh+(long)(16*(wid&3)+(lane>>2))*PD+(wid>>2)*32+(lane&3)*8;
;   const unsigned kdst=lds0+LDS_K+wid*1024, vdst=lds0+LDS_V+wid*1024;
;     ...
;   const int vb0=(int)(lds0+LDS_V)+((lane>>4)&1)*32+(lane&3)*8+(4*hi+((lane&15)>>2))*64;
;   const char*Kbase=shm+LDS_K; bf16x8 kf[8];
;   const lds_cptr shm3=(lds_cptr)shm; const lds_cptr kp0=shm3+LDS_K+hi*1024+r32*16; const lds_cptr vp0=shm3+LDS_V+((lane>>4)&1)*32+(lane&3)*8+(4*hi+((lane&15)>>2))*64;
;   const int NT=(q0+QB)/KVBLK;
;   DMA_K(0,0);DMA_V(0,0);DMA_K(1,SLOTB);
;   bf16x8 qr[4];
;   #pragma unroll
;   for(int d0=0;d0<4;++d0)qr[d0]=*reinterpret_cast<const bf16x8*>(&Qw[(long)r32*PD+d0*16+hi*8]);
;   float mhat=0.f,l_reg=0.f;f32x16 o[2];o[0]=f32x16{};o[1]=f32x16{};f32x16 negm=f32x16{};asm volatile("":"+v"(negm));
;   const int qrel=wid*QBLK+r32;
;     ...
;   bool resc=false;
;     ...
;   f32x16 pA0,pA1,pB0,pB1;
;   int sl_prev=0,sl_cur=0,sl_next=SLOTB;
;     ...
;   DMA_K(2,2*SLOTB);
;   WAIT_BAR(3);
; __global__ void __launch_bounds__(NWAVES * 64, 2) hybrid_fwd(const Args A) {
;     ...
;         for (;;) {
;             if (F.wave == 0 && lane_id_asm() == 0) misc[0] = atomicAdd(F.ctl + CW_QUEUE + 64 * rep, 1u);
;             __syncthreads(); const unsigned idx = misc[0]; __syncthreads();
;             if (idx >= 1024u) break;
;             const int qb = 15 - (int)(idx >> 6), bhv = (int)(idx & 63u);
;             attn_body::attn_unit<8>(bhv >> 4, bhv & 15, qb, Pd, Pd, Pd, (attn_body::bf16*)(F.ws + WS_O), (char*)lds, F.wave);
.LBB0_1542:
	s_waitcnt lgkmcnt(0)
	s_barrier
	ds_read_b32 v0, v206
	s_mov_b64 s[6:7], -1
	s_waitcnt lgkmcnt(0)
	s_barrier
	v_cmp_lt_u32_e32 vcc, s51, v0
	v_readfirstlane_b32 s0, v0
	s_cbranch_vccnz .LBB0_1535
	s_and_b32 s6, s0, 7
	s_bfe_u32 s7, s0, 0x10005
	s_lshl_b32 s7, s7, 3
	s_or_b32 s6, s6, s7
	s_lshl_b32 s6, s6, 2
	s_bfe_u32 s7, s0, 0x20003
	s_or_b32 s6, s6, s7
	s_andn2_b32 s0, s0, 63
	s_or_b32 s0, s0, s6
	s_bfe_u32 s3, s0, 0x20004
	s_lshr_b32 s38, s0, 6
	s_lshl_b32 s6, s3, 12
	s_lshl_b32 s7, s0, 5
	s_lshl_b32 s37, s0, 6
	s_lshl_b32 s36, s38, 8
	s_and_b32 s7, s7, 0x180
	s_and_b32 s0, s37, 64
	s_add_i32 s6, s6, s43
	s_or_b32 s13, s7, s0
	s_sub_i32 s0, s6, s36
	s_addk_i32 s0, 0xf00
	s_mul_i32 s7, s0, 0xc00
	s_mul_hi_u32 s6, s0, 0xc00
	s_add_u32 s7, s33, s7
	s_addc_u32 s8, s42, s6
	s_and_b32 s9, s37, 0x380
	s_add_u32 s6, s7, s9
	s_addc_u32 s7, s8, 0
	s_mul_i32 s3, s3, 0xc00000
	s_add_u32 s3, s33, s3
	s_addc_u32 s35, s42, 0
	s_add_u32 s8, s3, s9
	s_addc_u32 s9, s35, 0
	s_lshl_b32 s13, s13, 1
	s_add_u32 s34, s3, s13
	v_mov_b64_e32 v[2:3], s[8:9]
	v_mbcnt_lo_u32_b32 v210, -1, 0
	v_mbcnt_hi_u32_b32 v210, -1, v210
	s_addc_u32 s35, s35, 0
	v_mad_i64_i32 v[2:3], s[8:9], v210, s52, v[2:3]
	s_mov_b32 s3, s1
	v_ashrrev_i32_e32 v0, 2, v210
	v_lshl_add_u64 v[16:17], v[2:3], 0, s[2:3]
	v_add_u32_e32 v0, s44, v0
	v_mov_b64_e32 v[2:3], s[34:35]
	v_lshlrev_b32_e32 v211, 3, v210
	v_mad_i64_i32 v[2:3], s[8:9], v0, s52, v[2:3]
	s_mov_b32 s13, s1
	v_and_b32_e32 v214, 24, v211
	v_lshl_add_u64 v[2:3], v[2:3], 0, s[12:13]
	v_lshlrev_b32_e32 v0, 1, v214
	v_lshl_add_u64 v[196:197], v[16:17], 0, s[10:11]
	v_lshl_add_u64 v[2:3], v[2:3], 0, v[0:1]
	s_mov_b32 s3, m0
	s_mov_b32 m0, s46
	s_nop 0
	global_load_lds_dwordx4 v[196:197], off
	s_mov_b32 m0, s3
	v_lshl_add_u64 v[34:35], v[2:3], 0, s[14:15]
	s_mov_b32 s3, m0
	s_mov_b32 m0, s47
	s_nop 0
	global_load_lds_dwordx4 v[34:35], off
	s_mov_b32 m0, s3
	s_cmp_lg_u32 0, -1
	s_cselect_b32 s3, 0, 0
	v_ashrrev_i32_e32 v213, 5, v210
	v_lshl_add_u64 v[2:3], v[16:17], 0, s[16:17]
	s_add_i32 s3, s3, s45
	v_and_b32_e32 v212, 31, v210
	s_add_i32 s8, s3, 0x2000
	s_mov_b32 s9, m0
	s_mov_b32 m0, s8
	s_nop 0
	global_load_lds_dwordx4 v[2:3], off
	s_mov_b32 m0, s9
	v_lshlrev_b32_e32 v2, 3, v213
	v_mul_u32_u24_e32 v0, 0x600, v212
	v_ashrrev_i32_e32 v3, 31, v2
	v_lshl_add_u64 v[2:3], v[2:3], 1, s[6:7]
	v_lshlrev_b32_e32 v0, 1, v0
	v_lshl_add_u64 v[18:19], v[2:3], 0, v[0:1]
	global_load_dwordx4 v[148:151], v[18:19], off
	global_load_dwordx4 v[140:143], v[18:19], off offset:32
	global_load_dwordx4 v[132:135], v[18:19], off offset:64
	global_load_dwordx4 v[128:131], v[18:19], off offset:96
	v_mov_b32_e32 v2, v1
	v_mov_b32_e32 v3, v1
	v_mov_b32_e32 v4, v1
	v_mov_b32_e32 v5, v1
	v_mov_b32_e32 v6, v1
	v_mov_b32_e32 v7, v1
	v_mov_b32_e32 v8, v1
	v_mov_b32_e32 v9, v1
	v_mov_b32_e32 v10, v1
	v_mov_b32_e32 v11, v1
	v_mov_b32_e32 v12, v1
	v_mov_b32_e32 v13, v1
	v_mov_b32_e32 v14, v1
	v_mov_b32_e32 v15, v1
	v_lshlrev_b32_e32 v0, 10, v213
	v_lshlrev_b32_e32 v18, 4, v212
	v_add3_u32 v220, 0, v0, v18
	v_lshl_add_u64 v[18:19], v[16:17], 0, s[18:19]
	v_mov_b32_e32 v0, v1
	v_mov_b64_e32 v[16:17], v[14:15]
	v_mov_b64_e32 v[14:15], v[12:13]
	v_mov_b64_e32 v[12:13], v[10:11]
	v_mov_b64_e32 v[10:11], v[8:9]
	v_mov_b64_e32 v[8:9], v[6:7]
	v_mov_b64_e32 v[6:7], v[4:5]
	v_mov_b64_e32 v[4:5], v[2:3]
	v_mov_b64_e32 v[2:3], v[0:1]
	s_addk_i32 s3, 0x4000
	s_mov_b32 s6, m0
	s_mov_b32 m0, s3
	s_nop 0
	global_load_lds_dwordx4 v[18:19], off
	s_mov_b32 m0, s6
	s_waitcnt vmcnt(3) lgkmcnt(0)
	s_barrier
; __device__ __forceinline__ void cmask(f32x16&p0,f32x16&p1,int jb,int qrel,int hi){
;   const float NEG=-INFINITY; int kb=64*jb+4*hi;
;   #pragma unroll
;   for(int r=0;r<16;++r){int kv=kb+(r&3)+8*(r>>2); if(kv>qrel)p0[r]=NEG; if(kv+32>qrel)p1[r]=NEG;}
; }
; __device__ __forceinline__ void qkt(f32x16&p0,f32x16&p1,const char*Kslot,const bf16x8*qr,const f32x16&negm,int r32,int hi){
;   const char*kb=Kslot+hi*1024+r32*16;
;   #pragma unroll
;   for(int d0=0;d0<4;++d0){
;     const bf16x8 b0=*reinterpret_cast<const bf16x8*>(kb+d0*2048);
;     const bf16x8 b1=*reinterpret_cast<const bf16x8*>(kb+d0*2048+512);
;     if(d0==0){p0=__builtin_amdgcn_mfma_f32_32x32x16_bf16(b0,qr[0],negm,0,0,0);p1=__builtin_amdgcn_mfma_f32_32x32x16_bf16(b1,qr[0],negm,0,0,0);}
;     else{p0=__builtin_amdgcn_mfma_f32_32x32x16_bf16(b0,qr[d0],p0,0,0,0);p1=__builtin_amdgcn_mfma_f32_32x32x16_bf16(b1,qr[d0],p1,0,0,0);}}
; }
	ds_read_b128 v[36:39], v220
	s_cmp_lg_u32 s38, 15
	s_cselect_b64 s[6:7], -1, 0
	v_or_b32_e32 v218, s43, v212
	v_lshlrev_b32_e32 v216, 2, v213
	s_and_b64 vcc, exec, s[6:7]
	s_waitcnt vmcnt(3) lgkmcnt(0)
	v_mfma_f32_32x32x16_bf16 v[18:33], v[36:39], v[148:151], v[2:17]
	ds_read_b128 v[36:39], v220 offset:512
	s_waitcnt lgkmcnt(0)
	v_mfma_f32_32x32x16_bf16 v[2:17], v[36:39], v[148:151], v[2:17]
	ds_read_b128 v[36:39], v220 offset:2048
	s_waitcnt vmcnt(2) lgkmcnt(0)
	v_mfma_f32_32x32x16_bf16 v[18:33], v[36:39], v[140:143], v[18:33]
	ds_read_b128 v[36:39], v220 offset:2560
	s_waitcnt lgkmcnt(0)
	v_mfma_f32_32x32x16_bf16 v[2:17], v[36:39], v[140:143], v[2:17]
	ds_read_b128 v[36:39], v220 offset:4096
	s_waitcnt vmcnt(1) lgkmcnt(0)
	v_mfma_f32_32x32x16_bf16 v[18:33], v[36:39], v[132:135], v[18:33]
	ds_read_b128 v[36:39], v220 offset:4608
	s_waitcnt lgkmcnt(0)
	v_mfma_f32_32x32x16_bf16 v[2:17], v[36:39], v[132:135], v[2:17]
	ds_read_b128 v[36:39], v220 offset:6144
	s_waitcnt vmcnt(0) lgkmcnt(0)
	v_mfma_f32_32x32x16_bf16 v[18:33], v[36:39], v[128:131], v[18:33]
	ds_read_b128 v[36:39], v220 offset:6656
	s_waitcnt lgkmcnt(0)
	v_mfma_f32_32x32x16_bf16 v[2:17], v[36:39], v[128:131], v[2:17]
	s_nop 15
	s_nop 7
	s_cbranch_vccnz .LBB0_1545
	v_add_u32_e32 v0, 32, v216
	v_cmp_le_i32_e32 vcc, v0, v218
	v_add_u32_e32 v0, 33, v216
	s_nop 7
	v_cndmask_b32_e32 v2, v207, v2, vcc
	v_cmp_lt_i32_e32 vcc, v216, v218
	s_nop 1
	v_cndmask_b32_e32 v19, v207, v19, vcc
	v_cmp_le_i32_e32 vcc, v216, v218
	s_nop 1
	v_cndmask_b32_e32 v18, v207, v18, vcc
	v_cmp_le_i32_e32 vcc, v0, v218
	v_or_b32_e32 v0, 2, v216
	s_nop 0
	v_cndmask_b32_e32 v3, v207, v3, vcc
	v_cmp_le_i32_e32 vcc, v0, v218
	v_add_u32_e32 v0, 34, v216
	s_nop 0
	v_cndmask_b32_e32 v20, v207, v20, vcc
	v_cmp_le_i32_e32 vcc, v0, v218
	v_or_b32_e32 v0, 3, v216
	s_nop 0
	v_cndmask_b32_e32 v4, v207, v4, vcc
	v_cmp_le_i32_e32 vcc, v0, v218
	v_add_u32_e32 v0, 35, v216
	s_nop 0
	v_cndmask_b32_e32 v21, v207, v21, vcc
	v_cmp_le_i32_e32 vcc, v0, v218
	v_add_u32_e32 v0, 8, v216
	s_nop 0
	v_cndmask_b32_e32 v5, v207, v5, vcc
	v_cmp_le_i32_e32 vcc, v0, v218
	v_add_u32_e32 v0, 40, v216
	s_nop 0
	v_cndmask_b32_e32 v22, v207, v22, vcc
	v_cmp_le_i32_e32 vcc, v0, v218
	v_add_u32_e32 v0, 9, v216
	s_nop 0
	v_cndmask_b32_e32 v6, v207, v6, vcc
	v_cmp_le_i32_e32 vcc, v0, v218
	v_add_u32_e32 v0, 41, v216
	s_nop 0
	v_cndmask_b32_e32 v23, v207, v23, vcc
	v_cmp_le_i32_e32 vcc, v0, v218
	v_add_u32_e32 v0, 10, v216
	s_nop 0
	v_cndmask_b32_e32 v7, v207, v7, vcc
	v_cmp_le_i32_e32 vcc, v0, v218
	v_add_u32_e32 v0, 42, v216
	s_nop 0
	v_cndmask_b32_e32 v24, v207, v24, vcc
	v_cmp_le_i32_e32 vcc, v0, v218
	v_add_u32_e32 v0, 11, v216
	s_nop 0
	v_cndmask_b32_e32 v8, v207, v8, vcc
	v_cmp_le_i32_e32 vcc, v0, v218
	v_add_u32_e32 v0, 43, v216
	s_nop 0
	v_cndmask_b32_e32 v25, v207, v25, vcc
	v_cmp_le_i32_e32 vcc, v0, v218
	v_add_u32_e32 v0, 16, v216
	s_nop 0
	v_cndmask_b32_e32 v9, v207, v9, vcc
	v_cmp_le_i32_e32 vcc, v0, v218
	v_add_u32_e32 v0, 48, v216
	s_nop 0
	v_cndmask_b32_e32 v26, v207, v26, vcc
	v_cmp_le_i32_e32 vcc, v0, v218
	v_add_u32_e32 v0, 17, v216
	s_nop 0
	v_cndmask_b32_e32 v10, v207, v10, vcc
	v_cmp_le_i32_e32 vcc, v0, v218
	v_add_u32_e32 v0, 49, v216
	s_nop 0
	v_cndmask_b32_e32 v27, v207, v27, vcc
	v_cmp_le_i32_e32 vcc, v0, v218
	v_add_u32_e32 v0, 18, v216
	s_nop 0
	v_cndmask_b32_e32 v11, v207, v11, vcc
	v_cmp_le_i32_e32 vcc, v0, v218
	v_add_u32_e32 v0, 50, v216
	s_nop 0
	v_cndmask_b32_e32 v28, v207, v28, vcc
	v_cmp_le_i32_e32 vcc, v0, v218
	v_add_u32_e32 v0, 19, v216
	s_nop 0
	v_cndmask_b32_e32 v12, v207, v12, vcc
	v_cmp_le_i32_e32 vcc, v0, v218
	v_add_u32_e32 v0, 51, v216
	s_nop 0
	v_cndmask_b32_e32 v29, v207, v29, vcc
	v_cmp_le_i32_e32 vcc, v0, v218
	v_add_u32_e32 v0, 24, v216
	s_nop 0
	v_cndmask_b32_e32 v13, v207, v13, vcc
	v_cmp_le_i32_e32 vcc, v0, v218
	v_add_u32_e32 v0, 56, v216
	s_nop 0
	v_cndmask_b32_e32 v30, v207, v30, vcc
	v_cmp_le_i32_e32 vcc, v0, v218
	v_add_u32_e32 v0, 25, v216
	s_nop 0
	v_cndmask_b32_e32 v14, v207, v14, vcc
	v_cmp_le_i32_e32 vcc, v0, v218
	v_add_u32_e32 v0, 57, v216
	s_nop 0
	v_cndmask_b32_e32 v31, v207, v31, vcc
	v_cmp_le_i32_e32 vcc, v0, v218
	v_add_u32_e32 v0, 26, v216
	s_nop 0
	v_cndmask_b32_e32 v15, v207, v15, vcc
	v_cmp_le_i32_e32 vcc, v0, v218
	v_add_u32_e32 v0, 58, v216
	s_nop 0
	v_cndmask_b32_e32 v32, v207, v32, vcc
	v_cmp_le_i32_e32 vcc, v0, v218
	v_add_u32_e32 v0, 27, v216
	s_nop 0
	v_cndmask_b32_e32 v16, v207, v16, vcc
	v_cmp_le_i32_e32 vcc, v0, v218
	v_add_u32_e32 v0, 59, v216
	s_nop 0
	v_cndmask_b32_e32 v33, v207, v33, vcc
	v_cmp_le_i32_e32 vcc, v0, v218
	s_nop 1
	v_cndmask_b32_e32 v17, v207, v17, vcc
